# attention steady steps: waves 0-3 (instead of 4-7) run the 3 post-barrier PV MFMAs + 6 exps before their closing barrier
# speedup vs baseline: 1.0053x; 1.0039x over previous
.LBB0_974:
	v_add_u32_e32 v94, s44, v241
	v_add_u32_e32 v102, s40, v228
	ds_read_b128 v[82:85], v94
	ds_read_b128 v[198:201], v94 offset:512
	ds_read_b128 v[202:205], v94 offset:2048
	ds_read_b128 v[194:197], v94 offset:2560
	s_waitcnt lgkmcnt(10)
	v_mfma_f32_32x32x16_bf16 v[50:65], v[150:153], v[106:109], v[50:65]
	v_exp_f32_e32 v130, v130
	v_exp_f32_e32 v131, v131
	v_exp_f32_e32 v132, v132
	ds_read_b128 v[190:193], v94 offset:4096
	ds_read_b128 v[186:189], v94 offset:4608
	ds_read_b128 v[182:185], v94 offset:6144
	ds_read_b128 v[178:181], v94 offset:6656
	ds_read_b64_tr_b16 v[98:99],v102 offset:3072
	ds_read_b64_tr_b16 v[100:101],v102 offset:3584
	ds_read_b64_tr_b16 v[94:95],v102 offset:2048
	ds_read_b64_tr_b16 v[96:97],v102 offset:2560
	s_waitcnt lgkmcnt(15)
	v_mfma_f32_32x32x16_bf16 v[34:49], v[150:153], v[110:113], v[34:49]
	v_exp_f32_e32 v133, v133
	v_exp_f32_e32 v134, v134
	v_exp_f32_e32 v135, v135
	s_waitcnt lgkmcnt(14)
	v_mfma_f32_32x32x16_bf16 v[50:65], v[146:149], v[86:89], v[50:65]
	v_exp_f32_e32 v136, v136
	v_exp_f32_e32 v137, v137
	v_exp_f32_e32 v138, v138
	ds_read_b64_tr_b16 v[86:87],v102 offset:0
	ds_read_b64_tr_b16 v[88:89],v102 offset:512
	s_waitcnt lgkmcnt(14)
	v_mfma_f32_32x32x16_bf16 v[34:49], v[146:149], v[90:93], v[34:49]
	v_exp_f32_e32 v139, v139
	v_exp_f32_e32 v140, v140
	v_exp_f32_e32 v141, v141
	ds_read_b64_tr_b16 v[90:91],v102 offset:1024
	ds_read_b64_tr_b16 v[92:93],v102 offset:1536
	s_waitcnt lgkmcnt(6)
	v_mfma_f32_32x32x16_bf16 v[18:33], v[146:149], v[98:101], v[18:33]
	v_exp_f32_e32 v142, v142
	v_exp_f32_e32 v143, v143
	v_exp_f32_e32 v144, v144
	ds_read_b64_tr_b16 v[98:99],v102 offset:7168
	ds_read_b64_tr_b16 v[100:101],v102 offset:7680
	s_waitcnt lgkmcnt(6)
	v_mfma_f32_32x32x16_bf16 v[18:33], v[150:153], v[94:97], v[18:33]
	v_exp_f32_e32 v145, v145
	v_exp_f32_e32 v114, v114
	v_exp_f32_e32 v115, v115
	ds_read_b64_tr_b16 v[94:95],v102 offset:6144
	ds_read_b64_tr_b16 v[96:97],v102 offset:6656
	s_waitcnt lgkmcnt(6)
	v_mfma_f32_32x32x16_bf16 v[18:33], v[158:161], v[86:89], v[18:33]
	v_exp_f32_e32 v116, v116
	v_exp_f32_e32 v117, v117
	v_exp_f32_e32 v118, v118
	ds_read_b64_tr_b16 v[86:87],v102 offset:4096
	ds_read_b64_tr_b16 v[88:89],v102 offset:4608
	s_waitcnt lgkmcnt(6)
	v_mfma_f32_32x32x16_bf16 v[18:33], v[154:157], v[90:93], v[18:33]
	v_exp_f32_e32 v119, v119
	v_exp_f32_e32 v120, v120
	v_exp_f32_e32 v121, v121
	ds_read_b64_tr_b16 v[90:91],v102 offset:5120
	ds_read_b64_tr_b16 v[92:93],v102 offset:5632
	s_waitcnt lgkmcnt(6)
	v_mfma_f32_32x32x16_bf16 v[2:17], v[146:149], v[98:101], v[2:17]
	v_exp_f32_e32 v122, v122
	v_exp_f32_e32 v123, v123
	s_cmp_ge_u32 s83, 0x1000
	s_cbranch_scc1 .Lstg_lead_0
	s_waitcnt lgkmcnt(0)
	s_andn2_b64 vcc, exec, s[2:3]
	v_add_u32_e32 v229, s94, v243
	v_mfma_f32_32x32x16_bf16 v[2:17], v[150:153], v[94:97], v[2:17]
	v_exp_f32_e32 v124, v124
	v_exp_f32_e32 v125, v125
	v_mfma_f32_32x32x16_bf16 v[2:17], v[158:161], v[86:89], v[2:17]
	v_exp_f32_e32 v126, v126
	v_exp_f32_e32 v127, v127
	v_mfma_f32_32x32x16_bf16 v[2:17], v[154:157], v[90:93], v[2:17]
	v_exp_f32_e32 v128, v128
	v_exp_f32_e32 v129, v129
	s_waitcnt vmcnt(3)
	s_barrier
	s_branch .Lstg_join_0

.LBB0_977:
	v_add_u32_e32 v126, s40, v241
	v_add_u32_e32 v130, s45, v228
	ds_read_b128 v[206:209], v126
	ds_read_b128 v[202:205], v126 offset:512
	ds_read_b128 v[198:201], v126 offset:2048
	ds_read_b128 v[194:197], v126 offset:2560
	s_waitcnt lgkmcnt(10)
	v_mfma_f32_32x32x16_bf16 v[50:65], v[150:153], v[138:141], v[50:65]
	v_exp_f32_e32 v98, v98
	v_exp_f32_e32 v99, v99
	v_exp_f32_e32 v100, v100
	ds_read_b128 v[190:193], v126 offset:4096
	ds_read_b128 v[186:189], v126 offset:4608
	ds_read_b128 v[182:185], v126 offset:6144
	ds_read_b128 v[178:181], v126 offset:6656
	ds_read_b64_tr_b16 v[126:127],v130 offset:3072
	ds_read_b64_tr_b16 v[128:129],v130 offset:3584
	s_waitcnt lgkmcnt(14)
	v_mfma_f32_32x32x16_bf16 v[34:49], v[150:153], v[114:117], v[34:49]
	v_exp_f32_e32 v101, v101
	v_exp_f32_e32 v102, v102
	v_exp_f32_e32 v103, v103
	ds_read_b64_tr_b16 v[114:115],v130 offset:0
	ds_read_b64_tr_b16 v[116:117],v130 offset:512
	s_waitcnt lgkmcnt(14)
	v_mfma_f32_32x32x16_bf16 v[50:65], v[146:149], v[118:121], v[50:65]
	v_exp_f32_e32 v104, v104
	v_exp_f32_e32 v105, v105
	v_exp_f32_e32 v106, v106
	ds_read_b64_tr_b16 v[118:119],v130 offset:1024
	ds_read_b64_tr_b16 v[120:121],v130 offset:1536
	s_waitcnt lgkmcnt(14)
	v_mfma_f32_32x32x16_bf16 v[34:49], v[146:149], v[122:125], v[34:49]
	v_exp_f32_e32 v107, v107
	v_exp_f32_e32 v108, v108
	v_exp_f32_e32 v109, v109
	ds_read_b64_tr_b16 v[122:123],v130 offset:2048
	ds_read_b64_tr_b16 v[124:125],v130 offset:2560
	s_waitcnt lgkmcnt(6)
	v_mfma_f32_32x32x16_bf16 v[18:33], v[146:149], v[126:129], v[18:33]
	v_exp_f32_e32 v110, v110
	v_exp_f32_e32 v111, v111
	v_exp_f32_e32 v112, v112
	ds_read_b64_tr_b16 v[126:127],v130 offset:7168
	ds_read_b64_tr_b16 v[128:129],v130 offset:7680
	s_waitcnt lgkmcnt(6)
	v_mfma_f32_32x32x16_bf16 v[18:33], v[158:161], v[114:117], v[18:33]
	v_exp_f32_e32 v113, v113
	v_exp_f32_e32 v82, v82
	v_exp_f32_e32 v83, v83
	ds_read_b64_tr_b16 v[114:115],v130 offset:4096
	ds_read_b64_tr_b16 v[116:117],v130 offset:4608
	s_waitcnt lgkmcnt(6)
	v_mfma_f32_32x32x16_bf16 v[18:33], v[154:157], v[118:121], v[18:33]
	v_exp_f32_e32 v84, v84
	v_exp_f32_e32 v85, v85
	v_exp_f32_e32 v86, v86
	ds_read_b64_tr_b16 v[118:119],v130 offset:5120
	ds_read_b64_tr_b16 v[120:121],v130 offset:5632
	s_waitcnt lgkmcnt(6)
	v_mfma_f32_32x32x16_bf16 v[18:33], v[150:153], v[122:125], v[18:33]
	v_exp_f32_e32 v87, v87
	v_exp_f32_e32 v88, v88
	v_exp_f32_e32 v89, v89
	ds_read_b64_tr_b16 v[122:123],v130 offset:6144
	ds_read_b64_tr_b16 v[124:125],v130 offset:6656
	s_waitcnt lgkmcnt(6)
	v_mfma_f32_32x32x16_bf16 v[2:17], v[146:149], v[126:129], v[2:17]
	v_exp_f32_e32 v90, v90
	v_exp_f32_e32 v91, v91
	s_cmp_ge_u32 s83, 0x1000
	s_cbranch_scc1 .Lstg_lead_1
	s_waitcnt lgkmcnt(0)
	s_andn2_b64 vcc, exec, s[2:3]
	v_mfma_f32_32x32x16_bf16 v[2:17], v[158:161], v[114:117], v[2:17]
	v_exp_f32_e32 v92, v92
	v_exp_f32_e32 v93, v93
	v_mfma_f32_32x32x16_bf16 v[2:17], v[154:157], v[118:121], v[2:17]
	v_exp_f32_e32 v94, v94
	v_exp_f32_e32 v95, v95
	v_mfma_f32_32x32x16_bf16 v[2:17], v[150:153], v[122:125], v[2:17]
	v_exp_f32_e32 v96, v96
	v_exp_f32_e32 v97, v97
	s_waitcnt vmcnt(3)
	s_barrier
	s_branch .Lstg_join_1

.LBB0_1080:
	v_add_u32_e32 v94, s43, v241
	v_add_u32_e32 v102, s40, v228
	ds_read_b128 v[82:85], v94
	ds_read_b128 v[198:201], v94 offset:512
	ds_read_b128 v[202:205], v94 offset:2048
	ds_read_b128 v[194:197], v94 offset:2560
	s_waitcnt lgkmcnt(10)
	v_mfma_f32_32x32x16_bf16 v[50:65], v[158:161], v[106:109], v[50:65]
	v_exp_f32_e32 v130, v130
	v_exp_f32_e32 v131, v131
	v_exp_f32_e32 v132, v132
	ds_read_b128 v[190:193], v94 offset:4096
	ds_read_b128 v[186:189], v94 offset:4608
	ds_read_b128 v[182:185], v94 offset:6144
	ds_read_b128 v[178:181], v94 offset:6656
	ds_read_b64_tr_b16 v[98:99],v102 offset:3072
	ds_read_b64_tr_b16 v[100:101],v102 offset:3584
	ds_read_b64_tr_b16 v[94:95],v102 offset:2048
	ds_read_b64_tr_b16 v[96:97],v102 offset:2560
	s_waitcnt lgkmcnt(15)
	v_mfma_f32_32x32x16_bf16 v[34:49], v[158:161], v[110:113], v[34:49]
	v_exp_f32_e32 v133, v133
	v_exp_f32_e32 v134, v134
	v_exp_f32_e32 v135, v135
	s_waitcnt lgkmcnt(14)
	v_mfma_f32_32x32x16_bf16 v[50:65], v[154:157], v[86:89], v[50:65]
	v_exp_f32_e32 v136, v136
	v_exp_f32_e32 v137, v137
	v_exp_f32_e32 v138, v138
	ds_read_b64_tr_b16 v[86:87],v102 offset:0
	ds_read_b64_tr_b16 v[88:89],v102 offset:512
	s_waitcnt lgkmcnt(14)
	v_mfma_f32_32x32x16_bf16 v[34:49], v[154:157], v[90:93], v[34:49]
	v_exp_f32_e32 v139, v139
	v_exp_f32_e32 v140, v140
	v_exp_f32_e32 v141, v141
	ds_read_b64_tr_b16 v[90:91],v102 offset:1024
	ds_read_b64_tr_b16 v[92:93],v102 offset:1536
	s_waitcnt lgkmcnt(6)
	v_mfma_f32_32x32x16_bf16 v[18:33], v[154:157], v[98:101], v[18:33]
	v_exp_f32_e32 v142, v142
	v_exp_f32_e32 v143, v143
	v_exp_f32_e32 v144, v144
	ds_read_b64_tr_b16 v[98:99],v102 offset:7168
	ds_read_b64_tr_b16 v[100:101],v102 offset:7680
	s_waitcnt lgkmcnt(6)
	v_mfma_f32_32x32x16_bf16 v[18:33], v[158:161], v[94:97], v[18:33]
	v_exp_f32_e32 v145, v145
	v_exp_f32_e32 v114, v114
	v_exp_f32_e32 v115, v115
	ds_read_b64_tr_b16 v[94:95],v102 offset:6144
	ds_read_b64_tr_b16 v[96:97],v102 offset:6656
	s_waitcnt lgkmcnt(6)
	v_mfma_f32_32x32x16_bf16 v[18:33], v[166:169], v[86:89], v[18:33]
	v_exp_f32_e32 v116, v116
	v_exp_f32_e32 v117, v117
	v_exp_f32_e32 v118, v118
	ds_read_b64_tr_b16 v[86:87],v102 offset:4096
	ds_read_b64_tr_b16 v[88:89],v102 offset:4608
	s_waitcnt lgkmcnt(6)
	v_mfma_f32_32x32x16_bf16 v[18:33], v[162:165], v[90:93], v[18:33]
	v_exp_f32_e32 v119, v119
	v_exp_f32_e32 v120, v120
	v_exp_f32_e32 v121, v121
	ds_read_b64_tr_b16 v[90:91],v102 offset:5120
	ds_read_b64_tr_b16 v[92:93],v102 offset:5632
	s_waitcnt lgkmcnt(6)
	v_mfma_f32_32x32x16_bf16 v[2:17], v[154:157], v[98:101], v[2:17]
	v_exp_f32_e32 v122, v122
	v_exp_f32_e32 v123, v123
	s_cmp_ge_u32 s44, 0x1000
	s_cbranch_scc1 .Lstg_lead_2
	s_waitcnt lgkmcnt(0)
	s_andn2_b64 vcc, exec, s[2:3]
	v_add_u32_e32 v229, s39, v243
	v_mfma_f32_32x32x16_bf16 v[2:17], v[158:161], v[94:97], v[2:17]
	v_exp_f32_e32 v124, v124
	v_exp_f32_e32 v125, v125
	v_mfma_f32_32x32x16_bf16 v[2:17], v[166:169], v[86:89], v[2:17]
	v_exp_f32_e32 v126, v126
	v_exp_f32_e32 v127, v127
	v_mfma_f32_32x32x16_bf16 v[2:17], v[162:165], v[90:93], v[2:17]
	v_exp_f32_e32 v128, v128
	v_exp_f32_e32 v129, v129
	s_waitcnt vmcnt(3)
	s_barrier
	s_branch .Lstg_join_2

.LBB0_1083:
	v_add_u32_e32 v126, s40, v241
	v_add_u32_e32 v130, s47, v228
	ds_read_b128 v[206:209], v126
	ds_read_b128 v[198:201], v126 offset:512
	ds_read_b128 v[202:205], v126 offset:2048
	ds_read_b128 v[194:197], v126 offset:2560
	s_waitcnt lgkmcnt(10)
	v_mfma_f32_32x32x16_bf16 v[50:65], v[158:161], v[138:141], v[50:65]
	v_exp_f32_e32 v98, v98
	v_exp_f32_e32 v99, v99
	v_exp_f32_e32 v100, v100
	ds_read_b128 v[190:193], v126 offset:4096
	ds_read_b128 v[186:189], v126 offset:4608
	ds_read_b128 v[182:185], v126 offset:6144
	ds_read_b128 v[178:181], v126 offset:6656
	ds_read_b64_tr_b16 v[126:127],v130 offset:3072
	ds_read_b64_tr_b16 v[128:129],v130 offset:3584
	s_waitcnt lgkmcnt(14)
	v_mfma_f32_32x32x16_bf16 v[34:49], v[158:161], v[114:117], v[34:49]
	v_exp_f32_e32 v101, v101
	v_exp_f32_e32 v102, v102
	v_exp_f32_e32 v103, v103
	ds_read_b64_tr_b16 v[114:115],v130 offset:0
	ds_read_b64_tr_b16 v[116:117],v130 offset:512
	s_waitcnt lgkmcnt(14)
	v_mfma_f32_32x32x16_bf16 v[50:65], v[154:157], v[118:121], v[50:65]
	v_exp_f32_e32 v104, v104
	v_exp_f32_e32 v105, v105
	v_exp_f32_e32 v106, v106
	ds_read_b64_tr_b16 v[118:119],v130 offset:1024
	ds_read_b64_tr_b16 v[120:121],v130 offset:1536
	s_waitcnt lgkmcnt(14)
	v_mfma_f32_32x32x16_bf16 v[34:49], v[154:157], v[122:125], v[34:49]
	v_exp_f32_e32 v107, v107
	v_exp_f32_e32 v108, v108
	v_exp_f32_e32 v109, v109
	ds_read_b64_tr_b16 v[122:123],v130 offset:2048
	ds_read_b64_tr_b16 v[124:125],v130 offset:2560
	s_waitcnt lgkmcnt(6)
	v_mfma_f32_32x32x16_bf16 v[18:33], v[154:157], v[126:129], v[18:33]
	v_exp_f32_e32 v110, v110
	v_exp_f32_e32 v111, v111
	v_exp_f32_e32 v112, v112
	ds_read_b64_tr_b16 v[126:127],v130 offset:7168
	ds_read_b64_tr_b16 v[128:129],v130 offset:7680
	s_waitcnt lgkmcnt(6)
	v_mfma_f32_32x32x16_bf16 v[18:33], v[166:169], v[114:117], v[18:33]
	v_exp_f32_e32 v113, v113
	v_exp_f32_e32 v82, v82
	v_exp_f32_e32 v83, v83
	ds_read_b64_tr_b16 v[114:115],v130 offset:4096
	ds_read_b64_tr_b16 v[116:117],v130 offset:4608
	s_waitcnt lgkmcnt(6)
	v_mfma_f32_32x32x16_bf16 v[18:33], v[162:165], v[118:121], v[18:33]
	v_exp_f32_e32 v84, v84
	v_exp_f32_e32 v85, v85
	v_exp_f32_e32 v86, v86
	ds_read_b64_tr_b16 v[118:119],v130 offset:5120
	ds_read_b64_tr_b16 v[120:121],v130 offset:5632
	s_waitcnt lgkmcnt(6)
	v_mfma_f32_32x32x16_bf16 v[18:33], v[158:161], v[122:125], v[18:33]
	v_exp_f32_e32 v87, v87
	v_exp_f32_e32 v88, v88
	v_exp_f32_e32 v89, v89
	ds_read_b64_tr_b16 v[122:123],v130 offset:6144
	ds_read_b64_tr_b16 v[124:125],v130 offset:6656
	s_waitcnt lgkmcnt(6)
	v_mfma_f32_32x32x16_bf16 v[2:17], v[154:157], v[126:129], v[2:17]
	v_exp_f32_e32 v90, v90
	v_exp_f32_e32 v91, v91
	s_cmp_ge_u32 s44, 0x1000
	s_cbranch_scc1 .Lstg_lead_3
	s_waitcnt lgkmcnt(0)
	s_andn2_b64 vcc, exec, s[2:3]
	v_mfma_f32_32x32x16_bf16 v[2:17], v[166:169], v[114:117], v[2:17]
	v_exp_f32_e32 v92, v92
	v_exp_f32_e32 v93, v93
	v_mfma_f32_32x32x16_bf16 v[2:17], v[162:165], v[118:121], v[2:17]
	v_exp_f32_e32 v94, v94
	v_exp_f32_e32 v95, v95
	v_mfma_f32_32x32x16_bf16 v[2:17], v[158:161], v[122:125], v[2:17]
	v_exp_f32_e32 v96, v96
	v_exp_f32_e32 v97, v97
	s_waitcnt vmcnt(3)
	s_barrier
	s_branch .Lstg_join_3
